# plus: mix2 consumer steps no longer wait on their own store acknowledgements (all loads of a pass retired once before the first step)
# baseline (speedup 1.0000x reference)
.LBB0_932:
	s_or_b64 exec, exec, s[12:13]
	s_add_i32 s17, s17, 1
	v_cmp_lt_u32_e64 s[42:43], s17, v184
	v_lshl_add_u64 v[172:173], v[72:73], 0, v[34:35]
	s_and_saveexec_b64 s[12:13], s[42:43]
	s_cbranch_execz .LBB0_949
	s_waitcnt vmcnt(0)
	v_add_co_u32_e32 v76, vcc, 0x41100000, v172
	s_nop 1
	v_addc_co_u32_e32 v77, vcc, 0, v173, vcc
	global_load_dwordx2 v[76:77], v[76:77], off
	s_or_b64 exec, exec, s[12:13]
	s_waitcnt vmcnt(0)
	s_and_saveexec_b64 s[12:13], s[72:73]
	s_cbranch_execnz .LBB0_950

.LBB0_935:
	v_add_co_u32_e32 v188, vcc, 0x43900000, v206
	v_cvt_pk_bf16_f32 v186, v164, v165
	v_cvt_pk_bf16_f32 v187, v162, v163
	s_nop 1
	v_addc_co_u32_e32 v189, vcc, 0, v207, vcc
	global_store_dwordx2 v[188:189], v[186:187], off
	v_cvt_f32_f16_sdwa v187, v104 dst_sel:DWORD dst_unused:UNUSED_PAD src0_sel:WORD_1
	v_cvt_f32_f16_sdwa v189, v105 dst_sel:DWORD dst_unused:UNUSED_PAD src0_sel:WORD_1
	v_cvt_f32_f16_e32 v186, v104
	v_cvt_f32_f16_e32 v188, v105
	v_pk_fma_f32 v[164:165], v[36:37], v[164:165], v[186:187]
	v_pk_fma_f32 v[162:163], v[70:71], v[162:163], v[188:189]
	s_or_b64 exec, exec, s[12:13]
	s_and_saveexec_b64 s[12:13], s[68:69]
	s_cbranch_execnz .LBB0_952

.LBB0_937:
	v_add_co_u32_e32 v188, vcc, 0x43900000, v202
	v_cvt_pk_bf16_f32 v186, v164, v165
	v_cvt_pk_bf16_f32 v187, v162, v163
	s_nop 1
	v_addc_co_u32_e32 v189, vcc, 0, v203, vcc
	global_store_dwordx2 v[188:189], v[186:187], off
	v_cvt_f32_f16_sdwa v187, v100 dst_sel:DWORD dst_unused:UNUSED_PAD src0_sel:WORD_1
	v_cvt_f32_f16_sdwa v189, v101 dst_sel:DWORD dst_unused:UNUSED_PAD src0_sel:WORD_1
	v_cvt_f32_f16_e32 v186, v100
	v_cvt_f32_f16_e32 v188, v101
	v_pk_fma_f32 v[164:165], v[36:37], v[164:165], v[186:187]
	v_pk_fma_f32 v[162:163], v[70:71], v[162:163], v[188:189]
	s_or_b64 exec, exec, s[12:13]
	s_and_saveexec_b64 s[12:13], s[64:65]
	s_cbranch_execnz .LBB0_954

.LBB0_939:
	v_add_co_u32_e32 v188, vcc, 0x43900000, v198
	v_cvt_pk_bf16_f32 v186, v164, v165
	v_cvt_pk_bf16_f32 v187, v162, v163
	s_nop 1
	v_addc_co_u32_e32 v189, vcc, 0, v199, vcc
	global_store_dwordx2 v[188:189], v[186:187], off
	v_cvt_f32_f16_sdwa v187, v96 dst_sel:DWORD dst_unused:UNUSED_PAD src0_sel:WORD_1
	v_cvt_f32_f16_sdwa v189, v97 dst_sel:DWORD dst_unused:UNUSED_PAD src0_sel:WORD_1
	v_cvt_f32_f16_e32 v186, v96
	v_cvt_f32_f16_e32 v188, v97
	v_pk_fma_f32 v[164:165], v[36:37], v[164:165], v[186:187]
	v_pk_fma_f32 v[162:163], v[70:71], v[162:163], v[188:189]
	s_or_b64 exec, exec, s[12:13]
	s_and_saveexec_b64 s[12:13], s[60:61]
	s_cbranch_execnz .LBB0_956

.LBB0_941:
	v_add_co_u32_e32 v188, vcc, 0x43900000, v194
	v_cvt_pk_bf16_f32 v186, v164, v165
	v_cvt_pk_bf16_f32 v187, v162, v163
	s_nop 1
	v_addc_co_u32_e32 v189, vcc, 0, v195, vcc
	global_store_dwordx2 v[188:189], v[186:187], off
	v_cvt_f32_f16_sdwa v187, v92 dst_sel:DWORD dst_unused:UNUSED_PAD src0_sel:WORD_1
	v_cvt_f32_f16_sdwa v189, v93 dst_sel:DWORD dst_unused:UNUSED_PAD src0_sel:WORD_1
	v_cvt_f32_f16_e32 v186, v92
	v_cvt_f32_f16_e32 v188, v93
	v_pk_fma_f32 v[164:165], v[36:37], v[164:165], v[186:187]
	v_pk_fma_f32 v[162:163], v[70:71], v[162:163], v[188:189]
	s_or_b64 exec, exec, s[12:13]
	s_and_saveexec_b64 s[12:13], s[56:57]
	s_cbranch_execnz .LBB0_958

.LBB0_943:
	v_add_co_u32_e32 v188, vcc, 0x43900000, v190
	v_cvt_pk_bf16_f32 v186, v164, v165
	v_cvt_pk_bf16_f32 v187, v162, v163
	s_nop 1
	v_addc_co_u32_e32 v189, vcc, 0, v191, vcc
	global_store_dwordx2 v[188:189], v[186:187], off
	v_cvt_f32_f16_sdwa v187, v88 dst_sel:DWORD dst_unused:UNUSED_PAD src0_sel:WORD_1
	v_cvt_f32_f16_sdwa v189, v89 dst_sel:DWORD dst_unused:UNUSED_PAD src0_sel:WORD_1
	v_cvt_f32_f16_e32 v186, v88
	v_cvt_f32_f16_e32 v188, v89
	v_pk_fma_f32 v[164:165], v[36:37], v[164:165], v[186:187]
	v_pk_fma_f32 v[162:163], v[70:71], v[162:163], v[188:189]
	s_or_b64 exec, exec, s[12:13]
	s_and_saveexec_b64 s[12:13], s[52:53]
	s_cbranch_execnz .LBB0_960

.LBB0_945:
	v_add_co_u32_e32 v180, vcc, 0x43900000, v180
	v_cvt_pk_bf16_f32 v182, v164, v165
	v_cvt_pk_bf16_f32 v183, v162, v163
	s_nop 1
	v_addc_co_u32_e32 v181, vcc, 0, v181, vcc
	global_store_dwordx2 v[180:181], v[182:183], off
	v_cvt_f32_f16_sdwa v181, v84 dst_sel:DWORD dst_unused:UNUSED_PAD src0_sel:WORD_1
	v_cvt_f32_f16_sdwa v183, v85 dst_sel:DWORD dst_unused:UNUSED_PAD src0_sel:WORD_1
	v_cvt_f32_f16_e32 v180, v84
	v_cvt_f32_f16_e32 v182, v85
	v_pk_fma_f32 v[164:165], v[36:37], v[164:165], v[180:181]
	v_pk_fma_f32 v[162:163], v[70:71], v[162:163], v[182:183]
	s_or_b64 exec, exec, s[12:13]
	s_and_saveexec_b64 s[12:13], s[48:49]
	s_cbranch_execnz .LBB0_962

.LBB0_947:
	v_add_co_u32_e32 v176, vcc, 0x43900000, v176
	v_cvt_pk_bf16_f32 v178, v164, v165
	v_cvt_pk_bf16_f32 v179, v162, v163
	s_nop 1
	v_addc_co_u32_e32 v177, vcc, 0, v177, vcc
	global_store_dwordx2 v[176:177], v[178:179], off
	v_cvt_f32_f16_sdwa v177, v80 dst_sel:DWORD dst_unused:UNUSED_PAD src0_sel:WORD_1
	v_cvt_f32_f16_sdwa v179, v81 dst_sel:DWORD dst_unused:UNUSED_PAD src0_sel:WORD_1
	v_cvt_f32_f16_e32 v176, v80
	v_cvt_f32_f16_e32 v178, v81
	v_pk_fma_f32 v[164:165], v[36:37], v[164:165], v[176:177]
	v_pk_fma_f32 v[162:163], v[70:71], v[162:163], v[178:179]
	s_or_b64 exec, exec, s[12:13]
	s_and_saveexec_b64 s[12:13], s[44:45]
	s_cbranch_execnz .LBB0_964

.LBB0_950:
	v_add_co_u32_e32 v188, vcc, 0x43900000, v208
	v_cvt_pk_bf16_f32 v186, v164, v165
	v_cvt_pk_bf16_f32 v187, v162, v163
	s_nop 1
	v_addc_co_u32_e32 v189, vcc, 0, v209, vcc
	global_store_dwordx2 v[188:189], v[186:187], off
	v_cvt_f32_f16_sdwa v187, v106 dst_sel:DWORD dst_unused:UNUSED_PAD src0_sel:WORD_1
	v_cvt_f32_f16_sdwa v189, v107 dst_sel:DWORD dst_unused:UNUSED_PAD src0_sel:WORD_1
	v_cvt_f32_f16_e32 v186, v106
	v_cvt_f32_f16_e32 v188, v107
	v_pk_fma_f32 v[164:165], v[36:37], v[164:165], v[186:187]
	v_pk_fma_f32 v[162:163], v[70:71], v[162:163], v[188:189]
	s_or_b64 exec, exec, s[12:13]
	s_and_saveexec_b64 s[12:13], s[70:71]
	s_cbranch_execnz .LBB0_935

.LBB0_952:
	v_add_co_u32_e32 v188, vcc, 0x43900000, v204
	v_cvt_pk_bf16_f32 v186, v164, v165
	v_cvt_pk_bf16_f32 v187, v162, v163
	s_nop 1
	v_addc_co_u32_e32 v189, vcc, 0, v205, vcc
	global_store_dwordx2 v[188:189], v[186:187], off
	v_cvt_f32_f16_sdwa v187, v102 dst_sel:DWORD dst_unused:UNUSED_PAD src0_sel:WORD_1
	v_cvt_f32_f16_sdwa v189, v103 dst_sel:DWORD dst_unused:UNUSED_PAD src0_sel:WORD_1
	v_cvt_f32_f16_e32 v186, v102
	v_cvt_f32_f16_e32 v188, v103
	v_pk_fma_f32 v[164:165], v[36:37], v[164:165], v[186:187]
	v_pk_fma_f32 v[162:163], v[70:71], v[162:163], v[188:189]
	s_or_b64 exec, exec, s[12:13]
	s_and_saveexec_b64 s[12:13], s[66:67]
	s_cbranch_execnz .LBB0_937

.LBB0_954:
	v_add_co_u32_e32 v188, vcc, 0x43900000, v200
	v_cvt_pk_bf16_f32 v186, v164, v165
	v_cvt_pk_bf16_f32 v187, v162, v163
	s_nop 1
	v_addc_co_u32_e32 v189, vcc, 0, v201, vcc
	global_store_dwordx2 v[188:189], v[186:187], off
	v_cvt_f32_f16_sdwa v187, v98 dst_sel:DWORD dst_unused:UNUSED_PAD src0_sel:WORD_1
	v_cvt_f32_f16_sdwa v189, v99 dst_sel:DWORD dst_unused:UNUSED_PAD src0_sel:WORD_1
	v_cvt_f32_f16_e32 v186, v98
	v_cvt_f32_f16_e32 v188, v99
	v_pk_fma_f32 v[164:165], v[36:37], v[164:165], v[186:187]
	v_pk_fma_f32 v[162:163], v[70:71], v[162:163], v[188:189]
	s_or_b64 exec, exec, s[12:13]
	s_and_saveexec_b64 s[12:13], s[62:63]
	s_cbranch_execnz .LBB0_939

.LBB0_956:
	v_add_co_u32_e32 v188, vcc, 0x43900000, v196
	v_cvt_pk_bf16_f32 v186, v164, v165
	v_cvt_pk_bf16_f32 v187, v162, v163
	s_nop 1
	v_addc_co_u32_e32 v189, vcc, 0, v197, vcc
	global_store_dwordx2 v[188:189], v[186:187], off
	v_cvt_f32_f16_sdwa v187, v94 dst_sel:DWORD dst_unused:UNUSED_PAD src0_sel:WORD_1
	v_cvt_f32_f16_sdwa v189, v95 dst_sel:DWORD dst_unused:UNUSED_PAD src0_sel:WORD_1
	v_cvt_f32_f16_e32 v186, v94
	v_cvt_f32_f16_e32 v188, v95
	v_pk_fma_f32 v[164:165], v[36:37], v[164:165], v[186:187]
	v_pk_fma_f32 v[162:163], v[70:71], v[162:163], v[188:189]
	s_or_b64 exec, exec, s[12:13]
	s_and_saveexec_b64 s[12:13], s[58:59]
	s_cbranch_execnz .LBB0_941

.LBB0_958:
	v_add_co_u32_e32 v188, vcc, 0x43900000, v192
	v_cvt_pk_bf16_f32 v186, v164, v165
	v_cvt_pk_bf16_f32 v187, v162, v163
	s_nop 1
	v_addc_co_u32_e32 v189, vcc, 0, v193, vcc
	global_store_dwordx2 v[188:189], v[186:187], off
	v_cvt_f32_f16_sdwa v187, v90 dst_sel:DWORD dst_unused:UNUSED_PAD src0_sel:WORD_1
	v_cvt_f32_f16_sdwa v189, v91 dst_sel:DWORD dst_unused:UNUSED_PAD src0_sel:WORD_1
	v_cvt_f32_f16_e32 v186, v90
	v_cvt_f32_f16_e32 v188, v91
	v_pk_fma_f32 v[164:165], v[36:37], v[164:165], v[186:187]
	v_pk_fma_f32 v[162:163], v[70:71], v[162:163], v[188:189]
	s_or_b64 exec, exec, s[12:13]
	s_and_saveexec_b64 s[12:13], s[54:55]
	s_cbranch_execnz .LBB0_943

.LBB0_960:
	v_add_co_u32_e32 v182, vcc, 0x43900000, v182
	v_cvt_pk_bf16_f32 v186, v164, v165
	v_cvt_pk_bf16_f32 v187, v162, v163
	s_nop 1
	v_addc_co_u32_e32 v183, vcc, 0, v183, vcc
	global_store_dwordx2 v[182:183], v[186:187], off
	v_cvt_f32_f16_sdwa v183, v86 dst_sel:DWORD dst_unused:UNUSED_PAD src0_sel:WORD_1
	v_cvt_f32_f16_sdwa v187, v87 dst_sel:DWORD dst_unused:UNUSED_PAD src0_sel:WORD_1
	v_cvt_f32_f16_e32 v182, v86
	v_cvt_f32_f16_e32 v186, v87
	v_pk_fma_f32 v[164:165], v[36:37], v[164:165], v[182:183]
	v_pk_fma_f32 v[162:163], v[70:71], v[162:163], v[186:187]
	s_or_b64 exec, exec, s[12:13]
	s_and_saveexec_b64 s[12:13], s[50:51]
	s_cbranch_execnz .LBB0_945

.LBB0_962:
	v_add_co_u32_e32 v178, vcc, 0x43900000, v178
	v_cvt_pk_bf16_f32 v180, v164, v165
	v_cvt_pk_bf16_f32 v181, v162, v163
	s_nop 1
	v_addc_co_u32_e32 v179, vcc, 0, v179, vcc
	global_store_dwordx2 v[178:179], v[180:181], off
	v_cvt_f32_f16_sdwa v179, v82 dst_sel:DWORD dst_unused:UNUSED_PAD src0_sel:WORD_1
	v_cvt_f32_f16_sdwa v181, v83 dst_sel:DWORD dst_unused:UNUSED_PAD src0_sel:WORD_1
	v_cvt_f32_f16_e32 v178, v82
	v_cvt_f32_f16_e32 v180, v83
	v_pk_fma_f32 v[164:165], v[36:37], v[164:165], v[178:179]
	v_pk_fma_f32 v[162:163], v[70:71], v[162:163], v[180:181]
	s_or_b64 exec, exec, s[12:13]
	s_and_saveexec_b64 s[12:13], s[46:47]
	s_cbranch_execnz .LBB0_947

.LBB0_964:
	v_add_co_u32_e32 v174, vcc, 0x43900000, v174
	v_cvt_pk_bf16_f32 v176, v164, v165
	v_cvt_pk_bf16_f32 v177, v162, v163
	s_nop 1
	v_addc_co_u32_e32 v175, vcc, 0, v175, vcc
	global_store_dwordx2 v[174:175], v[176:177], off
	v_cvt_f32_f16_sdwa v175, v78 dst_sel:DWORD dst_unused:UNUSED_PAD src0_sel:WORD_1
	v_cvt_f32_f16_sdwa v177, v79 dst_sel:DWORD dst_unused:UNUSED_PAD src0_sel:WORD_1
	v_cvt_f32_f16_e32 v174, v78
	v_cvt_f32_f16_e32 v176, v79
	v_pk_fma_f32 v[164:165], v[36:37], v[164:165], v[174:175]
	v_pk_fma_f32 v[162:163], v[70:71], v[162:163], v[176:177]
	s_or_b64 exec, exec, s[12:13]
	s_and_saveexec_b64 s[12:13], s[42:43]
	s_cbranch_execz .LBB0_901
.LBB0_965:
	v_add_co_u32_e32 v172, vcc, 0x43900000, v172
	v_cvt_pk_bf16_f32 v174, v164, v165
	v_cvt_pk_bf16_f32 v175, v162, v163
	s_nop 1
	v_addc_co_u32_e32 v173, vcc, 0, v173, vcc
	global_store_dwordx2 v[172:173], v[174:175], off
	v_cvt_f32_f16_sdwa v173, v76 dst_sel:DWORD dst_unused:UNUSED_PAD src0_sel:WORD_1
	v_cvt_f32_f16_sdwa v175, v77 dst_sel:DWORD dst_unused:UNUSED_PAD src0_sel:WORD_1
	v_cvt_f32_f16_e32 v172, v76
	v_cvt_f32_f16_e32 v174, v77
	v_pk_fma_f32 v[164:165], v[36:37], v[164:165], v[172:173]
	v_pk_fma_f32 v[162:163], v[70:71], v[162:163], v[174:175]
	s_branch .LBB0_901

.LBB0_1008:
	s_or_b64 exec, exec, s[12:13]
	s_add_i32 s17, s17, 1
	v_cmp_lt_u32_e64 s[70:71], s17, v184
	v_lshl_add_u64 v[240:241], s[26:27], 0, v[142:143]
	s_and_saveexec_b64 s[12:13], s[70:71]
	s_cbranch_execz .LBB0_1025
	s_waitcnt vmcnt(0)
	v_add_co_u32_e32 v2, vcc, 0x3e800000, v240
	v_lshl_add_u64 v[4:5], s[26:27], 0, v[174:175]
	s_nop 0
	v_addc_co_u32_e32 v3, vcc, 0, v241, vcc
	global_load_dwordx2 v[136:137], v[2:3], off
	s_nop 0
	global_load_dwordx4 v[2:5], v[4:5], off
	s_or_b64 exec, exec, s[12:13]
	s_waitcnt vmcnt(0)
	s_and_saveexec_b64 s[12:13], s[40:41]
	s_cbranch_execnz .LBB0_1026

.LBB0_1011:
	v_add_co_u32_e32 v186, vcc, 0x3fd00000, v212
	v_cvt_pk_f16_f32 v37, v72, v73
	v_cvt_pk_f16_f32 v36, v70, v71
	v_addc_co_u32_e32 v187, vcc, 0, v213, vcc
	global_store_dwordx2 v[186:187], v[36:37], off
	v_cvt_f32_f16_sdwa v37, v108 dst_sel:DWORD dst_unused:UNUSED_PAD src0_sel:WORD_1
	v_cvt_f32_f16_sdwa v187, v109 dst_sel:DWORD dst_unused:UNUSED_PAD src0_sel:WORD_1
	v_cvt_f32_f16_e32 v36, v108
	v_cvt_f32_f16_e32 v186, v109
	v_pk_fma_f32 v[70:71], v[62:63], v[70:71], v[36:37]
	v_pk_fma_f32 v[72:73], v[64:65], v[72:73], v[186:187]
	s_or_b64 exec, exec, s[12:13]
	s_and_saveexec_b64 s[12:13], s[44:45]
	s_cbranch_execnz .LBB0_1028

.LBB0_1013:
	v_add_co_u32_e32 v186, vcc, 0x3fd00000, v216
	v_cvt_pk_f16_f32 v37, v72, v73
	v_cvt_pk_f16_f32 v36, v70, v71
	v_addc_co_u32_e32 v187, vcc, 0, v217, vcc
	global_store_dwordx2 v[186:187], v[36:37], off
	v_cvt_f32_f16_sdwa v37, v112 dst_sel:DWORD dst_unused:UNUSED_PAD src0_sel:WORD_1
	v_cvt_f32_f16_sdwa v187, v113 dst_sel:DWORD dst_unused:UNUSED_PAD src0_sel:WORD_1
	v_cvt_f32_f16_e32 v36, v112
	v_cvt_f32_f16_e32 v186, v113
	v_pk_fma_f32 v[70:71], v[54:55], v[70:71], v[36:37]
	v_pk_fma_f32 v[72:73], v[56:57], v[72:73], v[186:187]
	s_or_b64 exec, exec, s[12:13]
	s_and_saveexec_b64 s[12:13], s[48:49]
	s_cbranch_execnz .LBB0_1030

.LBB0_1015:
	v_add_co_u32_e32 v186, vcc, 0x3fd00000, v220
	v_cvt_pk_f16_f32 v37, v72, v73
	v_cvt_pk_f16_f32 v36, v70, v71
	v_addc_co_u32_e32 v187, vcc, 0, v221, vcc
	global_store_dwordx2 v[186:187], v[36:37], off
	v_cvt_f32_f16_sdwa v37, v116 dst_sel:DWORD dst_unused:UNUSED_PAD src0_sel:WORD_1
	v_cvt_f32_f16_sdwa v187, v117 dst_sel:DWORD dst_unused:UNUSED_PAD src0_sel:WORD_1
	v_cvt_f32_f16_e32 v36, v116
	v_cvt_f32_f16_e32 v186, v117
	v_pk_fma_f32 v[70:71], v[46:47], v[70:71], v[36:37]
	v_pk_fma_f32 v[72:73], v[48:49], v[72:73], v[186:187]
	s_or_b64 exec, exec, s[12:13]
	s_and_saveexec_b64 s[12:13], s[52:53]
	s_cbranch_execnz .LBB0_1032

.LBB0_1017:
	v_add_co_u32_e32 v186, vcc, 0x3fd00000, v224
	v_cvt_pk_f16_f32 v37, v72, v73
	v_cvt_pk_f16_f32 v36, v70, v71
	v_addc_co_u32_e32 v187, vcc, 0, v225, vcc
	global_store_dwordx2 v[186:187], v[36:37], off
	v_cvt_f32_f16_sdwa v37, v120 dst_sel:DWORD dst_unused:UNUSED_PAD src0_sel:WORD_1
	v_cvt_f32_f16_sdwa v187, v121 dst_sel:DWORD dst_unused:UNUSED_PAD src0_sel:WORD_1
	v_cvt_f32_f16_e32 v36, v120
	v_cvt_f32_f16_e32 v186, v121
	v_pk_fma_f32 v[70:71], v[38:39], v[70:71], v[36:37]
	v_pk_fma_f32 v[72:73], v[40:41], v[72:73], v[186:187]
	s_or_b64 exec, exec, s[12:13]
	s_and_saveexec_b64 s[12:13], s[56:57]
	s_cbranch_execnz .LBB0_1034

.LBB0_1019:
	v_add_co_u32_e32 v186, vcc, 0x3fd00000, v228
	v_cvt_pk_f16_f32 v37, v72, v73
	v_cvt_pk_f16_f32 v36, v70, v71
	v_addc_co_u32_e32 v187, vcc, 0, v229, vcc
	global_store_dwordx2 v[186:187], v[36:37], off
	v_cvt_f32_f16_sdwa v37, v124 dst_sel:DWORD dst_unused:UNUSED_PAD src0_sel:WORD_1
	v_cvt_f32_f16_sdwa v187, v125 dst_sel:DWORD dst_unused:UNUSED_PAD src0_sel:WORD_1
	v_cvt_f32_f16_e32 v36, v124
	v_cvt_f32_f16_e32 v186, v125
	v_pk_fma_f32 v[70:71], v[26:27], v[70:71], v[36:37]
	v_pk_fma_f32 v[72:73], v[28:29], v[72:73], v[186:187]
	s_or_b64 exec, exec, s[12:13]
	s_and_saveexec_b64 s[12:13], s[60:61]
	s_cbranch_execnz .LBB0_1036

.LBB0_1021:
	v_add_co_u32_e32 v186, vcc, 0x3fd00000, v232
	v_cvt_pk_f16_f32 v37, v72, v73
	v_cvt_pk_f16_f32 v36, v70, v71
	v_addc_co_u32_e32 v187, vcc, 0, v233, vcc
	global_store_dwordx2 v[186:187], v[36:37], off
	v_cvt_f32_f16_sdwa v37, v128 dst_sel:DWORD dst_unused:UNUSED_PAD src0_sel:WORD_1
	v_cvt_f32_f16_sdwa v187, v129 dst_sel:DWORD dst_unused:UNUSED_PAD src0_sel:WORD_1
	v_cvt_f32_f16_e32 v36, v128
	v_cvt_f32_f16_e32 v186, v129
	v_pk_fma_f32 v[70:71], v[18:19], v[70:71], v[36:37]
	v_pk_fma_f32 v[72:73], v[20:21], v[72:73], v[186:187]
	s_or_b64 exec, exec, s[12:13]
	s_and_saveexec_b64 s[12:13], s[64:65]
	s_cbranch_execnz .LBB0_1038

.LBB0_1023:
	v_add_co_u32_e32 v186, vcc, 0x3fd00000, v236
	v_cvt_pk_f16_f32 v37, v72, v73
	v_cvt_pk_f16_f32 v36, v70, v71
	v_addc_co_u32_e32 v187, vcc, 0, v237, vcc
	global_store_dwordx2 v[186:187], v[36:37], off
	v_cvt_f32_f16_sdwa v37, v132 dst_sel:DWORD dst_unused:UNUSED_PAD src0_sel:WORD_1
	v_cvt_f32_f16_sdwa v187, v133 dst_sel:DWORD dst_unused:UNUSED_PAD src0_sel:WORD_1
	v_cvt_f32_f16_e32 v36, v132
	v_cvt_f32_f16_e32 v186, v133
	v_pk_fma_f32 v[70:71], v[10:11], v[70:71], v[36:37]
	v_pk_fma_f32 v[72:73], v[12:13], v[72:73], v[186:187]
	s_or_b64 exec, exec, s[12:13]
	s_and_saveexec_b64 s[12:13], s[68:69]
	s_cbranch_execnz .LBB0_1040

.LBB0_1026:
	v_add_co_u32_e32 v36, vcc, 0x3fd00000, v36
	v_cvt_pk_f16_f32 v187, v72, v73
	v_cvt_pk_f16_f32 v186, v70, v71
	v_addc_co_u32_e32 v37, vcc, 0, v37, vcc
	global_store_dwordx2 v[36:37], v[186:187], off
	v_cvt_f32_f16_sdwa v37, v74 dst_sel:DWORD dst_unused:UNUSED_PAD src0_sel:WORD_1
	v_cvt_f32_f16_sdwa v187, v75 dst_sel:DWORD dst_unused:UNUSED_PAD src0_sel:WORD_1
	v_cvt_f32_f16_e32 v36, v74
	v_cvt_f32_f16_e32 v186, v75
	v_pk_fma_f32 v[70:71], v[70:71], v[66:67], v[36:37]
	v_pk_fma_f32 v[72:73], v[72:73], v[68:69], v[186:187]
	s_or_b64 exec, exec, s[12:13]
	s_and_saveexec_b64 s[12:13], s[42:43]
	s_cbranch_execnz .LBB0_1011

.LBB0_1028:
	v_add_co_u32_e32 v186, vcc, 0x3fd00000, v214
	v_cvt_pk_f16_f32 v37, v72, v73
	v_cvt_pk_f16_f32 v36, v70, v71
	v_addc_co_u32_e32 v187, vcc, 0, v215, vcc
	global_store_dwordx2 v[186:187], v[36:37], off
	v_cvt_f32_f16_sdwa v37, v110 dst_sel:DWORD dst_unused:UNUSED_PAD src0_sel:WORD_1
	v_cvt_f32_f16_sdwa v187, v111 dst_sel:DWORD dst_unused:UNUSED_PAD src0_sel:WORD_1
	v_cvt_f32_f16_e32 v36, v110
	v_cvt_f32_f16_e32 v186, v111
	v_pk_fma_f32 v[70:71], v[58:59], v[70:71], v[36:37]
	v_pk_fma_f32 v[72:73], v[60:61], v[72:73], v[186:187]
	s_or_b64 exec, exec, s[12:13]
	s_and_saveexec_b64 s[12:13], s[46:47]
	s_cbranch_execnz .LBB0_1013

.LBB0_1030:
	v_add_co_u32_e32 v186, vcc, 0x3fd00000, v218
	v_cvt_pk_f16_f32 v37, v72, v73
	v_cvt_pk_f16_f32 v36, v70, v71
	v_addc_co_u32_e32 v187, vcc, 0, v219, vcc
	global_store_dwordx2 v[186:187], v[36:37], off
	v_cvt_f32_f16_sdwa v37, v114 dst_sel:DWORD dst_unused:UNUSED_PAD src0_sel:WORD_1
	v_cvt_f32_f16_sdwa v187, v115 dst_sel:DWORD dst_unused:UNUSED_PAD src0_sel:WORD_1
	v_cvt_f32_f16_e32 v36, v114
	v_cvt_f32_f16_e32 v186, v115
	v_pk_fma_f32 v[70:71], v[50:51], v[70:71], v[36:37]
	v_pk_fma_f32 v[72:73], v[52:53], v[72:73], v[186:187]
	s_or_b64 exec, exec, s[12:13]
	s_and_saveexec_b64 s[12:13], s[50:51]
	s_cbranch_execnz .LBB0_1015

.LBB0_1032:
	v_add_co_u32_e32 v186, vcc, 0x3fd00000, v222
	v_cvt_pk_f16_f32 v37, v72, v73
	v_cvt_pk_f16_f32 v36, v70, v71
	v_addc_co_u32_e32 v187, vcc, 0, v223, vcc
	global_store_dwordx2 v[186:187], v[36:37], off
	v_cvt_f32_f16_sdwa v37, v118 dst_sel:DWORD dst_unused:UNUSED_PAD src0_sel:WORD_1
	v_cvt_f32_f16_sdwa v187, v119 dst_sel:DWORD dst_unused:UNUSED_PAD src0_sel:WORD_1
	v_cvt_f32_f16_e32 v36, v118
	v_cvt_f32_f16_e32 v186, v119
	v_pk_fma_f32 v[70:71], v[42:43], v[70:71], v[36:37]
	v_pk_fma_f32 v[72:73], v[44:45], v[72:73], v[186:187]
	s_or_b64 exec, exec, s[12:13]
	s_and_saveexec_b64 s[12:13], s[54:55]
	s_cbranch_execnz .LBB0_1017

.LBB0_1034:
	v_add_co_u32_e32 v186, vcc, 0x3fd00000, v226
	v_cvt_pk_f16_f32 v37, v72, v73
	v_cvt_pk_f16_f32 v36, v70, v71
	v_addc_co_u32_e32 v187, vcc, 0, v227, vcc
	global_store_dwordx2 v[186:187], v[36:37], off
	v_cvt_f32_f16_sdwa v37, v122 dst_sel:DWORD dst_unused:UNUSED_PAD src0_sel:WORD_1
	v_cvt_f32_f16_sdwa v187, v123 dst_sel:DWORD dst_unused:UNUSED_PAD src0_sel:WORD_1
	v_cvt_f32_f16_e32 v36, v122
	v_cvt_f32_f16_e32 v186, v123
	v_pk_fma_f32 v[70:71], v[30:31], v[70:71], v[36:37]
	v_pk_fma_f32 v[72:73], v[32:33], v[72:73], v[186:187]
	s_or_b64 exec, exec, s[12:13]
	s_and_saveexec_b64 s[12:13], s[58:59]
	s_cbranch_execnz .LBB0_1019

.LBB0_1036:
	v_add_co_u32_e32 v186, vcc, 0x3fd00000, v230
	v_cvt_pk_f16_f32 v37, v72, v73
	v_cvt_pk_f16_f32 v36, v70, v71
	v_addc_co_u32_e32 v187, vcc, 0, v231, vcc
	global_store_dwordx2 v[186:187], v[36:37], off
	v_cvt_f32_f16_sdwa v37, v126 dst_sel:DWORD dst_unused:UNUSED_PAD src0_sel:WORD_1
	v_cvt_f32_f16_sdwa v187, v127 dst_sel:DWORD dst_unused:UNUSED_PAD src0_sel:WORD_1
	v_cvt_f32_f16_e32 v36, v126
	v_cvt_f32_f16_e32 v186, v127
	v_pk_fma_f32 v[70:71], v[22:23], v[70:71], v[36:37]
	v_pk_fma_f32 v[72:73], v[24:25], v[72:73], v[186:187]
	s_or_b64 exec, exec, s[12:13]
	s_and_saveexec_b64 s[12:13], s[62:63]
	s_cbranch_execnz .LBB0_1021

.LBB0_1038:
	v_add_co_u32_e32 v186, vcc, 0x3fd00000, v234
	v_cvt_pk_f16_f32 v37, v72, v73
	v_cvt_pk_f16_f32 v36, v70, v71
	v_addc_co_u32_e32 v187, vcc, 0, v235, vcc
	global_store_dwordx2 v[186:187], v[36:37], off
	v_cvt_f32_f16_sdwa v37, v130 dst_sel:DWORD dst_unused:UNUSED_PAD src0_sel:WORD_1
	v_cvt_f32_f16_sdwa v187, v131 dst_sel:DWORD dst_unused:UNUSED_PAD src0_sel:WORD_1
	v_cvt_f32_f16_e32 v36, v130
	v_cvt_f32_f16_e32 v186, v131
	v_pk_fma_f32 v[70:71], v[14:15], v[70:71], v[36:37]
	v_pk_fma_f32 v[72:73], v[16:17], v[72:73], v[186:187]
	s_or_b64 exec, exec, s[12:13]
	s_and_saveexec_b64 s[12:13], s[66:67]
	s_cbranch_execnz .LBB0_1023

.LBB0_1040:
	v_add_co_u32_e32 v186, vcc, 0x3fd00000, v238
	v_cvt_pk_f16_f32 v37, v72, v73
	v_cvt_pk_f16_f32 v36, v70, v71
	v_addc_co_u32_e32 v187, vcc, 0, v239, vcc
	global_store_dwordx2 v[186:187], v[36:37], off
	v_cvt_f32_f16_sdwa v37, v134 dst_sel:DWORD dst_unused:UNUSED_PAD src0_sel:WORD_1
	v_cvt_f32_f16_sdwa v187, v135 dst_sel:DWORD dst_unused:UNUSED_PAD src0_sel:WORD_1
	v_cvt_f32_f16_e32 v36, v134
	v_cvt_f32_f16_e32 v186, v135
	v_pk_fma_f32 v[70:71], v[6:7], v[70:71], v[36:37]
	v_pk_fma_f32 v[72:73], v[8:9], v[72:73], v[186:187]
	s_or_b64 exec, exec, s[12:13]
	s_and_saveexec_b64 s[12:13], s[70:71]
	s_cbranch_execz .LBB0_977
.LBB0_1041:
	v_add_co_u32_e32 v186, vcc, 0x3fd00000, v240
	v_cvt_pk_f16_f32 v37, v72, v73
	v_cvt_pk_f16_f32 v36, v70, v71
	v_addc_co_u32_e32 v187, vcc, 0, v241, vcc
	global_store_dwordx2 v[186:187], v[36:37], off
	v_cvt_f32_f16_sdwa v37, v136 dst_sel:DWORD dst_unused:UNUSED_PAD src0_sel:WORD_1
	v_cvt_f32_f16_sdwa v187, v137 dst_sel:DWORD dst_unused:UNUSED_PAD src0_sel:WORD_1
	v_cvt_f32_f16_e32 v36, v136
	v_cvt_f32_f16_e32 v186, v137
	v_pk_fma_f32 v[70:71], v[2:3], v[70:71], v[36:37]
	v_pk_fma_f32 v[72:73], v[4:5], v[72:73], v[186:187]
	s_branch .LBB0_977
